# speedup vs baseline: 1.0029x; 1.0029x over previous
; DEV void sb_item(const Params& p, int item, unsigned char* smem) {
;     ...
;     if (it > 0) {
;       int all = 1;
; #pragma unroll
;       for (int i = 0; i < NW; ++i) all &= flags[((it - 1) & 1) * NW + i];
;       if (all) break;
;     }
.LBB0_436:
	s_and_b32 s1, s45, 8
	s_xor_b32 s6, s1, 8
	s_lshl_b32 s6, s6, 2
	s_or_b32 s6, s6, 0x16000
	v_mov_b32_e32 v64, s6
	s_waitcnt lgkmcnt(0)
	s_barrier
	ds_read_b128 v[200:203], v64
	ds_read_b128 v[204:207], v64 offset:16
	s_waitcnt lgkmcnt(0)
	v_and_b32_e32 v64, v200, v201
	v_and_b32_e32 v65, v202, v203
	v_and_b32_e32 v200, v204, v205
	v_and_b32_e32 v201, v206, v207
	v_and_b32_e32 v64, v64, v65
	v_and_b32_e32 v200, v200, v201
	v_and_b32_e32 v64, v64, v200
	v_and_b32_e32 v64, 1, v64
	v_cmp_eq_u32_e32 vcc, 1, v64
	v_cmp_eq_u32_e64 s[6:7], 0, v64
	s_cbranch_vccz .LBB0_438
	s_andn2_b64 vcc, exec, s[6:7]
	s_mov_b64 s[0:1], -1
	s_cbranch_vccnz .LBB0_433
	s_branch .LBB0_473
